# PEER selection: wave max/sum via DPP row reduction + readlane instead of ds_bpermute butterflies; pool-branch GEMM moved from phase 4 tail to idle filler blocks of phase 5
# speedup vs baseline: 1.1908x; 1.0127x over previous
.LBB0_635:
	s_mov_b32 s100, 0
	s_cmp_lt_i32 s92, 5
	s_cselect_b64 s[0:1], -1, 0
	s_cmp_gt_i32 s93, 4
	s_cselect_b64 s[4:5], -1, 0
	s_and_b64 s[0:1], s[0:1], s[4:5]
	s_andn2_b64 vcc, exec, s[0:1]
	s_cbranch_vccnz .LBB0_792
	s_cmp_gt_u32 s2, 63
	s_mov_b64 s[0:1], -1
	s_cbranch_scc1 .LBB0_639
	s_and_b64 vcc, exec, s[0:1]
	s_cbranch_vccnz .LBB0_734

.LBB0_728:
	s_abs_i32 s0, s3
	v_cvt_f32_u32_e32 v0, s0
	v_cvt_f32_u32_e32 v1, s3
	s_sub_i32 s4, 0, s0
	s_add_i32 s1, s3, s88
	v_rcp_iflag_f32_e32 v0, v0
	v_rcp_iflag_f32_e32 v1, v1
	v_readlane_b32 s88, v242, 25
	v_readlane_b32 s96, v242, 33
	v_mul_f32_e32 v0, 0x4f7ffffe, v0
	v_cvt_u32_f32_e32 v0, v0
	v_mul_f32_e32 v1, 0x4f7ffffe, v1
	v_cvt_u32_f32_e32 v1, v1
	v_readlane_b32 s89, v242, 26
	v_readfirstlane_b32 s5, v0
	s_mul_i32 s4, s4, s5
	s_mul_hi_u32 s4, s5, s4
	s_add_i32 s5, s5, s4
	s_lshr_b32 s4, s5, 21
	s_mul_i32 s4, s4, s0
	s_sub_i32 s4, 0x800, s4
	s_sub_i32 s5, s4, s0
	s_cmp_ge_u32 s4, s0
	s_cselect_b32 s4, s5, s4
	s_sub_i32 s5, s4, s0
	s_cmp_ge_u32 s4, s0
	s_cselect_b32 s0, s5, s4
	s_sub_i32 s4, 0, s3
	s_sub_i32 s0, s1, s0
	v_readfirstlane_b32 s1, v1
	s_mul_i32 s4, s4, s1
	s_mul_hi_u32 s4, s1, s4
	s_add_i32 s1, s1, s4
	s_mul_hi_u32 s1, s0, s1
	s_mul_i32 s1, s1, s3
	s_sub_i32 s0, s0, s1
	s_sub_i32 s1, s0, s3
	s_cmp_ge_u32 s0, s3
	s_cselect_b32 s0, s1, s0
	s_sub_i32 s1, s0, s3
	s_cmp_ge_u32 s0, s3
	s_cselect_b32 s4, s1, s0
	s_cmpk_gt_i32 s4, 0x20f
	v_readlane_b32 s90, v242, 27
	v_readlane_b32 s91, v242, 28
	v_readlane_b32 s92, v242, 29
	v_readlane_b32 s93, v242, 30
	v_readlane_b32 s94, v242, 31
	v_readlane_b32 s95, v242, 32
	v_readlane_b32 s97, v242, 34
	s_barrier
	s_cbranch_scc1 .LBB0_733
	s_cmp_lg_u32 s100, 1
	s_cbranch_scc1 .LBB0_733
	v_lshrrev_b32_e32 v1, 2, v218
	v_lshrrev_b32_e32 v0, 1, v218
	v_and_b32_e32 v1, 12, v1
	s_movk_i32 s0, 0x1c0
	v_and_or_b32 v0, v0, s0, v1
	v_and_b32_e32 v1, 0x4f, v218
	v_and_b32_e32 v2, 16, v218
	v_and_b32_e32 v3, 0x5f, v218
	v_bitop3_b32 v4, v1, v218, 16 bitop3:0x72
	v_bitop3_b32 v1, v1, v2, 48 bitop3:0x36
	v_lshlrev_b32_e32 v3, 2, v3
	v_lshlrev_b32_e32 v0, 9, v0
	v_lshlrev_b32_e32 v4, 2, v4
	v_lshlrev_b32_e32 v2, 2, v1
	v_mov_b32_e32 v1, 0
	s_movk_i32 s5, 0xa0
	v_add_u32_e32 v6, v3, v0
	v_add_u32_e32 v7, v4, v0
	v_add_u32_e32 v8, v2, v0

.LBB0_733:
	s_cmp_eq_u32 s100, 1
	s_cbranch_scc1 .LBB0_795
	s_branch .LBB0_638

.LBB0_834:
	v_readlane_b32 s94, v242, 31
	s_mov_b32 s100, 1
	s_sub_i32 s88, s2, 64
	s_nop 1
	s_sub_i32 s3, s94, 64
	s_branch .LBB0_728

.LBB0_1118:
	global_load_dword v41, v[38:39], off
	global_load_dword v40, v[36:37], off
	s_waitcnt vmcnt(2)
	v_add_f32_e32 v32, v42, v43
	v_cndmask_b32_e64 v44, v197, v32, s[4:5]
	ds_write_b32 v143, v44
	ds_read_b128 v[46:49], v136
	ds_read_b128 v[50:53], v136 offset:16
	ds_read_b128 v[54:57], v136 offset:32
	ds_read_b128 v[58:61], v136 offset:48
	ds_read_b128 v[62:65], v136 offset:64
	ds_read_b128 v[66:69], v136 offset:80
	ds_read_b128 v[74:77], v136 offset:96
	ds_read_b128 v[78:81], v136 offset:112
	ds_read_b128 v[82:85], v136 offset:128
	ds_read_b128 v[86:89], v136 offset:144
	ds_read_b128 v[90:93], v136 offset:160
	ds_read_b128 v[32:35], v136 offset:176
	v_mov_b32_e32 v70, 0
	v_mov_b32_e32 v71, 0
	s_waitcnt lgkmcnt(11)
	v_cmp_gt_f32_e64 s[0:1], v46, v44
	v_cmp_gt_f32_e64 s[22:23], v47, v44
	v_cmp_gt_f32_e64 s[98:99], v48, v44
	v_cmp_gt_f32_e64 s[100:101], v49, v44
	v_addc_co_u32_e64 v70, vcc, 0, v70, s[0:1]
	v_addc_co_u32_e64 v71, vcc, 0, v71, s[22:23]
	v_addc_co_u32_e64 v70, vcc, 0, v70, s[98:99]
	v_addc_co_u32_e64 v71, vcc, 0, v71, s[100:101]
	ds_read_b128 v[46:49], v136 offset:192
	s_waitcnt lgkmcnt(11)
	v_cmp_gt_f32_e64 s[0:1], v50, v44
	v_cmp_gt_f32_e64 s[22:23], v51, v44
	v_cmp_gt_f32_e64 s[98:99], v52, v44
	v_cmp_gt_f32_e64 s[100:101], v53, v44
	v_addc_co_u32_e64 v70, vcc, 0, v70, s[0:1]
	v_addc_co_u32_e64 v71, vcc, 0, v71, s[22:23]
	v_addc_co_u32_e64 v70, vcc, 0, v70, s[98:99]
	v_addc_co_u32_e64 v71, vcc, 0, v71, s[100:101]
	s_waitcnt lgkmcnt(10)
	v_cmp_gt_f32_e64 s[0:1], v54, v44
	v_cmp_gt_f32_e64 s[22:23], v55, v44
	v_cmp_gt_f32_e64 s[98:99], v56, v44
	v_cmp_gt_f32_e64 s[100:101], v57, v44
	v_addc_co_u32_e64 v70, vcc, 0, v70, s[0:1]
	v_addc_co_u32_e64 v71, vcc, 0, v71, s[22:23]
	v_addc_co_u32_e64 v70, vcc, 0, v70, s[98:99]
	v_addc_co_u32_e64 v71, vcc, 0, v71, s[100:101]
	s_waitcnt lgkmcnt(9)
	v_cmp_gt_f32_e64 s[0:1], v58, v44
	v_cmp_gt_f32_e64 s[22:23], v59, v44
	v_cmp_gt_f32_e64 s[98:99], v60, v44
	v_cmp_gt_f32_e64 s[100:101], v61, v44
	v_addc_co_u32_e64 v70, vcc, 0, v70, s[0:1]
	v_addc_co_u32_e64 v71, vcc, 0, v71, s[22:23]
	v_addc_co_u32_e64 v70, vcc, 0, v70, s[98:99]
	v_addc_co_u32_e64 v71, vcc, 0, v71, s[100:101]
	s_waitcnt lgkmcnt(8)
	v_cmp_gt_f32_e64 s[0:1], v62, v44
	v_cmp_gt_f32_e64 s[22:23], v63, v44
	v_cmp_gt_f32_e64 s[98:99], v64, v44
	v_cmp_gt_f32_e64 s[100:101], v65, v44
	v_addc_co_u32_e64 v70, vcc, 0, v70, s[0:1]
	v_addc_co_u32_e64 v71, vcc, 0, v71, s[22:23]
	v_addc_co_u32_e64 v70, vcc, 0, v70, s[98:99]
	v_addc_co_u32_e64 v71, vcc, 0, v71, s[100:101]
	s_waitcnt lgkmcnt(7)
	v_cmp_gt_f32_e64 s[0:1], v66, v44
	v_cmp_gt_f32_e64 s[22:23], v67, v44
	v_cmp_gt_f32_e64 s[98:99], v68, v44
	v_cmp_gt_f32_e64 s[100:101], v69, v44
	v_addc_co_u32_e64 v70, vcc, 0, v70, s[0:1]
	v_addc_co_u32_e64 v71, vcc, 0, v71, s[22:23]
	v_addc_co_u32_e64 v70, vcc, 0, v70, s[98:99]
	v_addc_co_u32_e64 v71, vcc, 0, v71, s[100:101]
	s_waitcnt lgkmcnt(6)
	v_cmp_gt_f32_e64 s[0:1], v74, v44
	v_cmp_gt_f32_e64 s[22:23], v75, v44
	v_cmp_gt_f32_e64 s[98:99], v76, v44
	v_cmp_gt_f32_e64 s[100:101], v77, v44
	v_addc_co_u32_e64 v70, vcc, 0, v70, s[0:1]
	v_addc_co_u32_e64 v71, vcc, 0, v71, s[22:23]
	v_addc_co_u32_e64 v70, vcc, 0, v70, s[98:99]
	v_addc_co_u32_e64 v71, vcc, 0, v71, s[100:101]
	s_waitcnt lgkmcnt(5)
	v_cmp_gt_f32_e64 s[0:1], v78, v44
	v_cmp_gt_f32_e64 s[22:23], v79, v44
	v_cmp_gt_f32_e64 s[98:99], v80, v44
	v_cmp_gt_f32_e64 s[100:101], v81, v44
	v_addc_co_u32_e64 v70, vcc, 0, v70, s[0:1]
	v_addc_co_u32_e64 v71, vcc, 0, v71, s[22:23]
	v_addc_co_u32_e64 v70, vcc, 0, v70, s[98:99]
	v_addc_co_u32_e64 v71, vcc, 0, v71, s[100:101]
	s_waitcnt lgkmcnt(4)
	v_cmp_gt_f32_e64 s[0:1], v82, v44
	v_cmp_gt_f32_e64 s[22:23], v83, v44
	v_cmp_gt_f32_e64 s[98:99], v84, v44
	v_cmp_gt_f32_e64 s[100:101], v85, v44
	v_addc_co_u32_e64 v70, vcc, 0, v70, s[0:1]
	v_addc_co_u32_e64 v71, vcc, 0, v71, s[22:23]
	v_addc_co_u32_e64 v70, vcc, 0, v70, s[98:99]
	v_addc_co_u32_e64 v71, vcc, 0, v71, s[100:101]
	s_waitcnt lgkmcnt(3)
	v_cmp_gt_f32_e64 s[0:1], v86, v44
	v_cmp_gt_f32_e64 s[22:23], v87, v44
	v_cmp_gt_f32_e64 s[98:99], v88, v44
	v_cmp_gt_f32_e64 s[100:101], v89, v44
	v_addc_co_u32_e64 v70, vcc, 0, v70, s[0:1]
	v_addc_co_u32_e64 v71, vcc, 0, v71, s[22:23]
	v_addc_co_u32_e64 v70, vcc, 0, v70, s[98:99]
	v_addc_co_u32_e64 v71, vcc, 0, v71, s[100:101]
	s_waitcnt lgkmcnt(2)
	v_cmp_gt_f32_e64 s[0:1], v90, v44
	v_cmp_gt_f32_e64 s[22:23], v91, v44
	v_cmp_gt_f32_e64 s[98:99], v92, v44
	v_cmp_gt_f32_e64 s[100:101], v93, v44
	v_addc_co_u32_e64 v70, vcc, 0, v70, s[0:1]
	v_addc_co_u32_e64 v71, vcc, 0, v71, s[22:23]
	v_addc_co_u32_e64 v70, vcc, 0, v70, s[98:99]
	v_addc_co_u32_e64 v71, vcc, 0, v71, s[100:101]
	s_waitcnt lgkmcnt(1)
	v_cmp_gt_f32_e64 s[0:1], v32, v44
	v_cmp_gt_f32_e64 s[22:23], v33, v44
	v_cmp_gt_f32_e64 s[98:99], v34, v44
	v_cmp_gt_f32_e64 s[100:101], v35, v44
	v_addc_co_u32_e64 v70, vcc, 0, v70, s[0:1]
	v_addc_co_u32_e64 v71, vcc, 0, v71, s[22:23]
	v_addc_co_u32_e64 v70, vcc, 0, v70, s[98:99]
	v_addc_co_u32_e64 v71, vcc, 0, v71, s[100:101]
	v_max_f32_dpp v45, v44, v44 quad_perm:[1,0,3,2] row_mask:0xf bank_mask:0xf
	s_nop 1
	v_max_f32_dpp v94, v45, v45 quad_perm:[2,3,0,1] row_mask:0xf bank_mask:0xf
	s_nop 1
	v_max_f32_dpp v45, v94, v94 row_half_mirror row_mask:0xf bank_mask:0xf
	s_nop 1
	v_max_f32_dpp v94, v45, v45 row_mirror row_mask:0xf bank_mask:0xf
	s_waitcnt lgkmcnt(0)
	v_cmp_gt_f32_e64 s[0:1], v46, v44
	v_cmp_gt_f32_e64 s[22:23], v47, v44
	v_cmp_gt_f32_e64 s[98:99], v48, v44
	v_cmp_gt_f32_e64 s[100:101], v49, v44
	v_addc_co_u32_e64 v70, vcc, 0, v70, s[0:1]
	v_addc_co_u32_e64 v71, vcc, 0, v71, s[22:23]
	v_addc_co_u32_e64 v70, vcc, 0, v70, s[98:99]
	v_addc_co_u32_e64 v71, vcc, 0, v71, s[100:101]
	v_readlane_b32 s0, v94, 0
	v_readlane_b32 s1, v94, 16
	v_readlane_b32 s22, v94, 32
	v_readlane_b32 s23, v94, 48
	v_add_u32_e32 v33, v70, v71
	s_nop 0
	v_mov_b32_e32 v32, s0
	v_max_f32_e32 v32, s1, v32
	v_max_f32_e32 v32, s22, v32
	v_max_f32_e32 v32, s23, v32
	v_sub_f32_e32 v32, v44, v32
	v_mul_f32_e32 v32, 0x3fb8aa3b, v32
	v_exp_f32_e32 v32, v32
	v_cmp_gt_i32_e32 vcc, 16, v33
	s_and_b64 vcc, s[4:5], vcc
	s_nop 0
	v_cndmask_b32_e32 v34, 0, v32, vcc
	s_mov_b64 s[100:101], vcc
	s_nop 0
	v_add_f32_dpp v35, v34, v34 quad_perm:[1,0,3,2] row_mask:0xf bank_mask:0xf
	s_nop 1
	v_add_f32_dpp v34, v35, v35 quad_perm:[2,3,0,1] row_mask:0xf bank_mask:0xf
	s_nop 1
	v_add_f32_dpp v35, v34, v34 row_half_mirror row_mask:0xf bank_mask:0xf
	s_nop 1
	v_add_f32_dpp v34, v35, v35 row_mirror row_mask:0xf bank_mask:0xf
	s_nop 1
	v_readlane_b32 s22, v34, 0
	v_readlane_b32 s23, v34, 16
	v_readlane_b32 s98, v34, 32
	v_readlane_b32 s99, v34, 48
	s_nop 1
	v_mov_b32_e32 v34, s22
	v_add_f32_e32 v34, s23, v34
	v_add_f32_e32 v34, s98, v34
	v_add_f32_e32 v34, s99, v34
	s_mov_b64 vcc, s[100:101]
	s_mov_b64 s[22:23], 0
	s_and_saveexec_b64 s[0:1], vcc
	s_cbranch_execz .Lpf_a_skip
	v_lshlrev_b32_e32 v35, 7, v42
	v_and_b32_e32 v51, 0x7f, v43
	v_div_scale_f32 v52, s[22:23], v34, v34, v32
	v_rcp_f32_e32 v53, v52
	v_and_or_b32 v35, v35, s31, v51
	v_add_u32_e32 v33, s24, v33
	v_lshl_add_u32 v33, v33, 2, v136
	v_fma_f32 v51, -v52, v53, 1.0
	v_fmac_f32_e32 v53, v51, v53
	v_div_scale_f32 v51, vcc, v32, v34, v32
	v_mul_f32_e32 v54, v51, v53
	v_fma_f32 v55, -v52, v54, v51
	v_fmac_f32_e32 v54, v55, v53
	v_fma_f32 v51, -v52, v54, v51
	v_div_fmas_f32 v51, v51, v53, v54
	v_div_fixup_f32 v32, v51, v34, v32
	ds_write2st64_b32 v33, v35, v32 offset0:1 offset1:3
	ds_read_b32 v34, v33 offset:256
	s_waitcnt lgkmcnt(0)
	v_cmp_ne_u32_e64 s[22:23], v34, v35

.LBB0_1322:
	s_waitcnt vmcnt(0)
	v_add_f32_e32 v32, v41, v40
	v_cndmask_b32_e64 v36, v197, v32, s[4:5]
	ds_write_b32 v143, v36
	ds_read_b128 v[46:49], v136
	ds_read_b128 v[50:53], v136 offset:16
	ds_read_b128 v[54:57], v136 offset:32
	ds_read_b128 v[58:61], v136 offset:48
	ds_read_b128 v[62:65], v136 offset:64
	ds_read_b128 v[66:69], v136 offset:80
	ds_read_b128 v[74:77], v136 offset:96
	ds_read_b128 v[78:81], v136 offset:112
	ds_read_b128 v[82:85], v136 offset:128
	ds_read_b128 v[86:89], v136 offset:144
	ds_read_b128 v[90:93], v136 offset:160
	ds_read_b128 v[32:35], v136 offset:176
	v_mov_b32_e32 v70, 0
	v_mov_b32_e32 v71, 0
	s_waitcnt lgkmcnt(11)
	v_cmp_gt_f32_e64 s[0:1], v46, v36
	v_cmp_gt_f32_e64 s[22:23], v47, v36
	v_cmp_gt_f32_e64 s[98:99], v48, v36
	v_cmp_gt_f32_e64 s[100:101], v49, v36
	v_addc_co_u32_e64 v70, vcc, 0, v70, s[0:1]
	v_addc_co_u32_e64 v71, vcc, 0, v71, s[22:23]
	v_addc_co_u32_e64 v70, vcc, 0, v70, s[98:99]
	v_addc_co_u32_e64 v71, vcc, 0, v71, s[100:101]
	ds_read_b128 v[46:49], v136 offset:192
	s_waitcnt lgkmcnt(11)
	v_cmp_gt_f32_e64 s[0:1], v50, v36
	v_cmp_gt_f32_e64 s[22:23], v51, v36
	v_cmp_gt_f32_e64 s[98:99], v52, v36
	v_cmp_gt_f32_e64 s[100:101], v53, v36
	v_addc_co_u32_e64 v70, vcc, 0, v70, s[0:1]
	v_addc_co_u32_e64 v71, vcc, 0, v71, s[22:23]
	v_addc_co_u32_e64 v70, vcc, 0, v70, s[98:99]
	v_addc_co_u32_e64 v71, vcc, 0, v71, s[100:101]
	s_waitcnt lgkmcnt(10)
	v_cmp_gt_f32_e64 s[0:1], v54, v36
	v_cmp_gt_f32_e64 s[22:23], v55, v36
	v_cmp_gt_f32_e64 s[98:99], v56, v36
	v_cmp_gt_f32_e64 s[100:101], v57, v36
	v_addc_co_u32_e64 v70, vcc, 0, v70, s[0:1]
	v_addc_co_u32_e64 v71, vcc, 0, v71, s[22:23]
	v_addc_co_u32_e64 v70, vcc, 0, v70, s[98:99]
	v_addc_co_u32_e64 v71, vcc, 0, v71, s[100:101]
	s_waitcnt lgkmcnt(9)
	v_cmp_gt_f32_e64 s[0:1], v58, v36
	v_cmp_gt_f32_e64 s[22:23], v59, v36
	v_cmp_gt_f32_e64 s[98:99], v60, v36
	v_cmp_gt_f32_e64 s[100:101], v61, v36
	v_addc_co_u32_e64 v70, vcc, 0, v70, s[0:1]
	v_addc_co_u32_e64 v71, vcc, 0, v71, s[22:23]
	v_addc_co_u32_e64 v70, vcc, 0, v70, s[98:99]
	v_addc_co_u32_e64 v71, vcc, 0, v71, s[100:101]
	s_waitcnt lgkmcnt(8)
	v_cmp_gt_f32_e64 s[0:1], v62, v36
	v_cmp_gt_f32_e64 s[22:23], v63, v36
	v_cmp_gt_f32_e64 s[98:99], v64, v36
	v_cmp_gt_f32_e64 s[100:101], v65, v36
	v_addc_co_u32_e64 v70, vcc, 0, v70, s[0:1]
	v_addc_co_u32_e64 v71, vcc, 0, v71, s[22:23]
	v_addc_co_u32_e64 v70, vcc, 0, v70, s[98:99]
	v_addc_co_u32_e64 v71, vcc, 0, v71, s[100:101]
	s_waitcnt lgkmcnt(7)
	v_cmp_gt_f32_e64 s[0:1], v66, v36
	v_cmp_gt_f32_e64 s[22:23], v67, v36
	v_cmp_gt_f32_e64 s[98:99], v68, v36
	v_cmp_gt_f32_e64 s[100:101], v69, v36
	v_addc_co_u32_e64 v70, vcc, 0, v70, s[0:1]
	v_addc_co_u32_e64 v71, vcc, 0, v71, s[22:23]
	v_addc_co_u32_e64 v70, vcc, 0, v70, s[98:99]
	v_addc_co_u32_e64 v71, vcc, 0, v71, s[100:101]
	s_waitcnt lgkmcnt(6)
	v_cmp_gt_f32_e64 s[0:1], v74, v36
	v_cmp_gt_f32_e64 s[22:23], v75, v36
	v_cmp_gt_f32_e64 s[98:99], v76, v36
	v_cmp_gt_f32_e64 s[100:101], v77, v36
	v_addc_co_u32_e64 v70, vcc, 0, v70, s[0:1]
	v_addc_co_u32_e64 v71, vcc, 0, v71, s[22:23]
	v_addc_co_u32_e64 v70, vcc, 0, v70, s[98:99]
	v_addc_co_u32_e64 v71, vcc, 0, v71, s[100:101]
	s_waitcnt lgkmcnt(5)
	v_cmp_gt_f32_e64 s[0:1], v78, v36
	v_cmp_gt_f32_e64 s[22:23], v79, v36
	v_cmp_gt_f32_e64 s[98:99], v80, v36
	v_cmp_gt_f32_e64 s[100:101], v81, v36
	v_addc_co_u32_e64 v70, vcc, 0, v70, s[0:1]
	v_addc_co_u32_e64 v71, vcc, 0, v71, s[22:23]
	v_addc_co_u32_e64 v70, vcc, 0, v70, s[98:99]
	v_addc_co_u32_e64 v71, vcc, 0, v71, s[100:101]
	s_waitcnt lgkmcnt(4)
	v_cmp_gt_f32_e64 s[0:1], v82, v36
	v_cmp_gt_f32_e64 s[22:23], v83, v36
	v_cmp_gt_f32_e64 s[98:99], v84, v36
	v_cmp_gt_f32_e64 s[100:101], v85, v36
	v_addc_co_u32_e64 v70, vcc, 0, v70, s[0:1]
	v_addc_co_u32_e64 v71, vcc, 0, v71, s[22:23]
	v_addc_co_u32_e64 v70, vcc, 0, v70, s[98:99]
	v_addc_co_u32_e64 v71, vcc, 0, v71, s[100:101]
	s_waitcnt lgkmcnt(3)
	v_cmp_gt_f32_e64 s[0:1], v86, v36
	v_cmp_gt_f32_e64 s[22:23], v87, v36
	v_cmp_gt_f32_e64 s[98:99], v88, v36
	v_cmp_gt_f32_e64 s[100:101], v89, v36
	v_addc_co_u32_e64 v70, vcc, 0, v70, s[0:1]
	v_addc_co_u32_e64 v71, vcc, 0, v71, s[22:23]
	v_addc_co_u32_e64 v70, vcc, 0, v70, s[98:99]
	v_addc_co_u32_e64 v71, vcc, 0, v71, s[100:101]
	s_waitcnt lgkmcnt(2)
	v_cmp_gt_f32_e64 s[0:1], v90, v36
	v_cmp_gt_f32_e64 s[22:23], v91, v36
	v_cmp_gt_f32_e64 s[98:99], v92, v36
	v_cmp_gt_f32_e64 s[100:101], v93, v36
	v_addc_co_u32_e64 v70, vcc, 0, v70, s[0:1]
	v_addc_co_u32_e64 v71, vcc, 0, v71, s[22:23]
	v_addc_co_u32_e64 v70, vcc, 0, v70, s[98:99]
	v_addc_co_u32_e64 v71, vcc, 0, v71, s[100:101]
	s_waitcnt lgkmcnt(1)
	v_cmp_gt_f32_e64 s[0:1], v32, v36
	v_cmp_gt_f32_e64 s[22:23], v33, v36
	v_cmp_gt_f32_e64 s[98:99], v34, v36
	v_cmp_gt_f32_e64 s[100:101], v35, v36
	v_addc_co_u32_e64 v70, vcc, 0, v70, s[0:1]
	v_addc_co_u32_e64 v71, vcc, 0, v71, s[22:23]
	v_addc_co_u32_e64 v70, vcc, 0, v70, s[98:99]
	v_addc_co_u32_e64 v71, vcc, 0, v71, s[100:101]
	v_max_f32_dpp v45, v36, v36 quad_perm:[1,0,3,2] row_mask:0xf bank_mask:0xf
	s_nop 1
	v_max_f32_dpp v94, v45, v45 quad_perm:[2,3,0,1] row_mask:0xf bank_mask:0xf
	s_nop 1
	v_max_f32_dpp v45, v94, v94 row_half_mirror row_mask:0xf bank_mask:0xf
	s_nop 1
	v_max_f32_dpp v94, v45, v45 row_mirror row_mask:0xf bank_mask:0xf
	s_waitcnt lgkmcnt(0)
	v_cmp_gt_f32_e64 s[0:1], v46, v36
	v_cmp_gt_f32_e64 s[22:23], v47, v36
	v_cmp_gt_f32_e64 s[98:99], v48, v36
	v_cmp_gt_f32_e64 s[100:101], v49, v36
	v_addc_co_u32_e64 v70, vcc, 0, v70, s[0:1]
	v_addc_co_u32_e64 v71, vcc, 0, v71, s[22:23]
	v_addc_co_u32_e64 v70, vcc, 0, v70, s[98:99]
	v_addc_co_u32_e64 v71, vcc, 0, v71, s[100:101]
	v_readlane_b32 s0, v94, 0
	v_readlane_b32 s1, v94, 16
	v_readlane_b32 s22, v94, 32
	v_readlane_b32 s23, v94, 48
	v_add_u32_e32 v33, v70, v71
	s_nop 0
	v_mov_b32_e32 v32, s0
	v_max_f32_e32 v32, s1, v32
	v_max_f32_e32 v32, s22, v32
	v_max_f32_e32 v32, s23, v32
	v_sub_f32_e32 v32, v36, v32
	v_mul_f32_e32 v32, 0x3fb8aa3b, v32
	v_exp_f32_e32 v32, v32
	v_cmp_gt_i32_e32 vcc, 16, v33
	s_and_b64 vcc, s[4:5], vcc
	s_nop 0
	v_cndmask_b32_e32 v34, 0, v32, vcc
	s_mov_b64 s[100:101], vcc
	s_nop 0
	v_add_f32_dpp v35, v34, v34 quad_perm:[1,0,3,2] row_mask:0xf bank_mask:0xf
	s_nop 1
	v_add_f32_dpp v34, v35, v35 quad_perm:[2,3,0,1] row_mask:0xf bank_mask:0xf
	s_nop 1
	v_add_f32_dpp v35, v34, v34 row_half_mirror row_mask:0xf bank_mask:0xf
	s_nop 1
	v_add_f32_dpp v34, v35, v35 row_mirror row_mask:0xf bank_mask:0xf
	s_nop 1
	v_readlane_b32 s22, v34, 0
	v_readlane_b32 s23, v34, 16
	v_readlane_b32 s98, v34, 32
	v_readlane_b32 s99, v34, 48
	s_nop 1
	v_mov_b32_e32 v34, s22
	v_add_f32_e32 v34, s23, v34
	v_add_f32_e32 v34, s98, v34
	v_add_f32_e32 v34, s99, v34
	s_mov_b64 vcc, s[100:101]
	s_mov_b64 s[22:23], 0
	s_and_saveexec_b64 s[0:1], vcc
	s_cbranch_execz .Lpf_b_skip
	v_lshlrev_b32_e32 v35, 7, v41
	v_and_b32_e32 v51, 0x7f, v40
	v_div_scale_f32 v52, s[22:23], v34, v34, v32
	v_rcp_f32_e32 v53, v52
	v_and_or_b32 v35, v35, s31, v51
	v_lshl_add_u32 v33, v33, 2, v136
	v_fma_f32 v51, -v52, v53, 1.0
	v_fmac_f32_e32 v53, v51, v53
	v_div_scale_f32 v51, vcc, v32, v34, v32
	v_mul_f32_e32 v54, v51, v53
	v_fma_f32 v55, -v52, v54, v51
	v_fmac_f32_e32 v54, v55, v53
	v_fma_f32 v51, -v52, v54, v51
	v_div_fmas_f32 v51, v51, v53, v54
	v_div_fixup_f32 v32, v51, v34, v32
	v_add_u32_e32 v33, 0xc0, v33
	ds_write2st64_b32 v33, v35, v32 offset0:2 offset1:4
	ds_read_b32 v34, v33 offset:512
	s_waitcnt lgkmcnt(0)
	v_cmp_ne_u32_e64 s[22:23], v34, v35
